# combo22 + E63: phase-0 silu(c) fill issues its 8 loads per thread up front instead of 8 dependent load-wait-silu-write round trips
# baseline (speedup 1.0000x reference)
.LBB0_421:
	v_mov_b32_e32 v32, v167
	s_movk_i32 s0, 0x1000
	s_nop 0
	v_readfirstlane_b32 s16, v32
	v_cmp_gt_i32_e32 vcc, s0, v32
	s_and_saveexec_b64 s[0:1], vcc
	s_cbranch_execz .LBB0_424
	v_readlane_b32 s84, v254, 4
	v_ashrrev_i32_e32 v33, 31, v32
	v_readlane_b32 s86, v254, 6
	v_readlane_b32 s87, v254, 7
	v_add_u32_e32 v2, 0xfffffe00, v32
	v_lshl_add_u32 v3, v32, 2, 16
	s_waitcnt lgkmcnt(0)
	v_lshl_add_u64 v[0:1], v[32:33], 2, s[86:87]
	s_mov_b64 s[8:9], 0
	v_readlane_b32 s85, v254, 5
	v_readlane_b32 s88, v254, 8
	v_readlane_b32 s89, v254, 9
	v_readlane_b32 s90, v254, 10
	v_readlane_b32 s91, v254, 11
	v_readlane_b32 s92, v254, 12
	v_readlane_b32 s93, v254, 13
	v_readlane_b32 s94, v254, 14
	v_readlane_b32 s95, v254, 15
	v_readlane_b32 s96, v254, 16
	v_readlane_b32 s97, v254, 17
	v_readlane_b32 s98, v254, 18
	v_readlane_b32 s99, v254, 19
	s_mov_b64 s[10:11], 0x1000
	global_load_dword v88, v[0:1], off
	global_load_dword v89, v[0:1], off offset:2048
	v_lshl_add_u64 v[0:1], v[0:1], 0, s[10:11]
	global_load_dword v90, v[0:1], off
	global_load_dword v91, v[0:1], off offset:2048
	v_lshl_add_u64 v[0:1], v[0:1], 0, s[10:11]
	global_load_dword v92, v[0:1], off
	global_load_dword v93, v[0:1], off offset:2048
	v_lshl_add_u64 v[0:1], v[0:1], 0, s[10:11]
	global_load_dword v94, v[0:1], off
	global_load_dword v95, v[0:1], off offset:2048
	s_waitcnt vmcnt(7)
	v_mul_f32_e32 v5, 0xbfb8aa3b, v88
	v_exp_f32_e32 v5, v5
	s_nop 0
	v_add_f32_e32 v5, 1.0, v5
	v_rcp_f32_e32 v5, v5
	s_nop 0
	v_mul_f32_e32 v4, v88, v5
	ds_write_b32 v3, v4
	s_waitcnt vmcnt(6)
	v_mul_f32_e32 v5, 0xbfb8aa3b, v89
	v_exp_f32_e32 v5, v5
	s_nop 0
	v_add_f32_e32 v5, 1.0, v5
	v_rcp_f32_e32 v5, v5
	s_nop 0
	v_mul_f32_e32 v4, v89, v5
	ds_write_b32 v3, v4 offset:2048
	s_waitcnt vmcnt(5)
	v_mul_f32_e32 v5, 0xbfb8aa3b, v90
	v_exp_f32_e32 v5, v5
	s_nop 0
	v_add_f32_e32 v5, 1.0, v5
	v_rcp_f32_e32 v5, v5
	s_nop 0
	v_mul_f32_e32 v4, v90, v5
	ds_write_b32 v3, v4 offset:4096
	s_waitcnt vmcnt(4)
	v_mul_f32_e32 v5, 0xbfb8aa3b, v91
	v_exp_f32_e32 v5, v5
	s_nop 0
	v_add_f32_e32 v5, 1.0, v5
	v_rcp_f32_e32 v5, v5
	s_nop 0
	v_mul_f32_e32 v4, v91, v5
	ds_write_b32 v3, v4 offset:6144
	s_waitcnt vmcnt(3)
	v_mul_f32_e32 v5, 0xbfb8aa3b, v92
	v_exp_f32_e32 v5, v5
	s_nop 0
	v_add_f32_e32 v5, 1.0, v5
	v_rcp_f32_e32 v5, v5
	s_nop 0
	v_mul_f32_e32 v4, v92, v5
	ds_write_b32 v3, v4 offset:8192
	s_waitcnt vmcnt(2)
	v_mul_f32_e32 v5, 0xbfb8aa3b, v93
	v_exp_f32_e32 v5, v5
	s_nop 0
	v_add_f32_e32 v5, 1.0, v5
	v_rcp_f32_e32 v5, v5
	s_nop 0
	v_mul_f32_e32 v4, v93, v5
	ds_write_b32 v3, v4 offset:10240
	s_waitcnt vmcnt(1)
	v_mul_f32_e32 v5, 0xbfb8aa3b, v94
	v_exp_f32_e32 v5, v5
	s_nop 0
	v_add_f32_e32 v5, 1.0, v5
	v_rcp_f32_e32 v5, v5
	s_nop 0
	v_mul_f32_e32 v4, v94, v5
	ds_write_b32 v3, v4 offset:12288
	s_waitcnt vmcnt(0)
	v_mul_f32_e32 v5, 0xbfb8aa3b, v95
	v_exp_f32_e32 v5, v5
	s_nop 0
	v_add_f32_e32 v5, 1.0, v5
	v_rcp_f32_e32 v5, v5
	s_nop 0
	v_mul_f32_e32 v4, v95, v5
	ds_write_b32 v3, v4 offset:14336
